# P4 pipelined v3: next item's 36 early loads issued right after the last MFMA pass, before the sum-of-squares reduce
# baseline (speedup 1.0000x reference)
; #define GAS __attribute__((address_space(1)))
; #define MFMA16(a, b, c) __builtin_amdgcn_mfma_f32_16x16x32_bf16((a), (b), (c), 0, 0, 0)
; __device__ __forceinline__ void p4_run(int gw, int NGW, const bf16_t* HGR, const bf16_t* DNR, const bf16_t* OLH, const bf16_t* OLD, const bf16_t* BNB, const float* hg_nw, const float* dn_nw, bf16_t* OAB, int lane) {
;     ...
;     for (int it = gw; it < 8192; it += NGW) {
;         asm volatile("" ::: "memory");
;         f32x4 o[8]; float ss = 0.f; u64_t gcur[8];
; #pragma unroll
;         for (int vt = 0; vt < 8; ++vt) gcur[vt] = P.gt8[vt];
; #pragma unroll
;         for (int vt = 0; vt < 4; ++vt) { f32x4 acc = unpack4(P.ol[vt]);
; #pragma unroll
;             for (int kb = 0; kb < 4; ++kb) acc = MFMA16(P.x[vt][kb], P.ya[kb], acc);
;             o[vt] = acc; ss += (acc[0] * acc[0] + acc[1] * acc[1]) + (acc[2] * acc[2] + acc[3] * acc[3]); }
;         asm volatile("" ::: "memory");
; #pragma unroll
;         for (int vt = 0; vt < 4; ++vt)
; #pragma unroll
;             for (int kb = 0; kb < 4; ++kb) P.x[vt][kb] = *(const GAS bf16x8*)(p.sn + (size_t)(((vt + 4) * 4 + kb) * 64 + lane) * 8);
;         f32x4 w8[8];
; #pragma unroll
;         for (int vt = 0; vt < 8; ++vt) w8[vt] = *(const GAS f32x4*)(p.nw + 16 * vt + 4 * g);
;         asm volatile("" ::: "memory");
; #pragma unroll
;         for (int vt = 0; vt < 4; ++vt) { f32x4 acc = unpack4(P.ol[vt + 4]);
; #pragma unroll
;             for (int kb = 0; kb < 4; ++kb) acc = MFMA16(P.x[vt][kb], P.ya[kb], acc);
;             o[vt + 4] = acc; ss += (acc[0] * acc[0] + acc[1] * acc[1]) + (acc[2] * acc[2] + acc[3] * acc[3]); }
;         const int t = 16 * p.mt + r;
;         bf16_t* orow2 = OAB + (size_t)(p.rb * 4 + p.mt) * 32768 + r * 1024 + p.br * 512 + p.h * 128 + 16 * (g & 1) + 8 * (g >> 1);
;         asm volatile("" :: "v"(o[4][0]), "v"(o[5][0]), "v"(o[6][0]), "v"(o[7][0]) : "memory");
;         if (it + NGW < 8192) { p = p4_ptrs(it + NGW, HGR, DNR, OLH, OLD, BNB, hg_nw, dn_nw); p4_load_a(P, p, lane); }
;         asm volatile("" ::: "memory");
;         ss += __shfl_xor(ss, 16); ss += __shfl_xor(ss, 32);
;         const float rstd = rsqrtf(ss * (1.f / 128.f) + RMS_EPS);
.Lp4n_item:
	global_load_dwordx4 v[18:21], v210, s[74:75]
	s_add_u32 s74, s74, 0x1000
	s_addc_u32 s75, s75, 0
	global_load_dwordx4 v[34:37], v210, s[74:75]
	s_add_u32 s74, s74, 0x1000
	s_addc_u32 s75, s75, 0
	global_load_dwordx4 v[50:53], v210, s[74:75]
	s_add_u32 s74, s74, 0x1000
	s_addc_u32 s75, s75, 0
	global_load_dwordx4 v[66:69], v210, s[74:75]
	s_add_u32 s74, s74, 0x1000
	s_addc_u32 s75, s75, 0
	global_load_dwordx4 v[82:85], v210, s[74:75]
	s_add_u32 s74, s74, 0x1000
	s_addc_u32 s75, s75, 0
	global_load_dwordx4 v[98:101], v210, s[74:75]
	s_add_u32 s74, s74, 0x1000
	s_addc_u32 s75, s75, 0
	global_load_dwordx4 v[114:117], v210, s[74:75]
	s_add_u32 s74, s74, 0x1000
	s_addc_u32 s75, s75, 0
	global_load_dwordx4 v[130:133], v210, s[74:75]
	global_load_dwordx2 v[162:163], v213, s[18:19]
	global_load_dwordx2 v[164:165], v213, s[18:19] offset:32
	global_load_dwordx2 v[166:167], v213, s[18:19] offset:64
	global_load_dwordx2 v[168:169], v213, s[18:19] offset:96
	global_load_dwordx2 v[170:171], v213, s[18:19] offset:128
	global_load_dwordx2 v[172:173], v213, s[18:19] offset:160
	global_load_dwordx2 v[174:175], v213, s[18:19] offset:192
	global_load_dwordx2 v[176:177], v213, s[18:19] offset:224
	s_waitcnt vmcnt(8)
	v_lshlrev_b32_e32 v178, 16, v146
	v_and_b32_e32 v179, 0xffff0000, v146
	v_lshlrev_b32_e32 v180, 16, v147
	v_and_b32_e32 v181, 0xffff0000, v147
	v_lshlrev_b32_e32 v182, 16, v148
	v_and_b32_e32 v183, 0xffff0000, v148
	v_lshlrev_b32_e32 v184, 16, v149
	v_and_b32_e32 v185, 0xffff0000, v149
	v_lshlrev_b32_e32 v186, 16, v150
	v_and_b32_e32 v187, 0xffff0000, v150
	v_lshlrev_b32_e32 v188, 16, v151
	v_and_b32_e32 v189, 0xffff0000, v151
	v_lshlrev_b32_e32 v190, 16, v152
	v_and_b32_e32 v191, 0xffff0000, v152
	v_lshlrev_b32_e32 v192, 16, v153
	v_and_b32_e32 v193, 0xffff0000, v153
	v_lshlrev_b32_e32 v194, 16, v154
	v_and_b32_e32 v195, 0xffff0000, v154
	v_lshlrev_b32_e32 v196, 16, v155
	v_and_b32_e32 v197, 0xffff0000, v155
	v_lshlrev_b32_e32 v198, 16, v156
	v_and_b32_e32 v199, 0xffff0000, v156
	v_lshlrev_b32_e32 v200, 16, v157
	v_and_b32_e32 v201, 0xffff0000, v157
	v_lshlrev_b32_e32 v202, 16, v158
	v_and_b32_e32 v203, 0xffff0000, v158
	v_lshlrev_b32_e32 v204, 16, v159
	v_and_b32_e32 v205, 0xffff0000, v159
	v_lshlrev_b32_e32 v206, 16, v160
	v_and_b32_e32 v207, 0xffff0000, v160
	v_lshlrev_b32_e32 v208, 16, v161
	v_and_b32_e32 v209, 0xffff0000, v161
	s_nop 1
	v_mfma_f32_16x16x32_bf16 v[178:181], v[18:21], v[2:5], v[178:181]
	v_mfma_f32_16x16x32_bf16 v[182:185], v[34:37], v[2:5], v[182:185]
	v_mfma_f32_16x16x32_bf16 v[186:189], v[50:53], v[2:5], v[186:189]
	v_mfma_f32_16x16x32_bf16 v[190:193], v[66:69], v[2:5], v[190:193]
	v_mfma_f32_16x16x32_bf16 v[194:197], v[82:85], v[2:5], v[194:197]
	v_mfma_f32_16x16x32_bf16 v[198:201], v[98:101], v[2:5], v[198:201]
	v_mfma_f32_16x16x32_bf16 v[202:205], v[114:117], v[2:5], v[202:205]
	v_mfma_f32_16x16x32_bf16 v[206:209], v[130:133], v[2:5], v[206:209]
	global_load_dwordx4 v[18:21], v215, s[44:45]
	global_load_dwordx4 v[34:37], v215, s[44:45] offset:64
	global_load_dwordx4 v[50:53], v215, s[44:45] offset:128
	global_load_dwordx4 v[66:69], v215, s[44:45] offset:192
	global_load_dwordx4 v[82:85], v215, s[44:45] offset:256
	global_load_dwordx4 v[98:101], v215, s[44:45] offset:320
	global_load_dwordx4 v[114:117], v215, s[44:45] offset:384
	global_load_dwordx4 v[130:133], v215, s[44:45] offset:448
	v_mfma_f32_16x16x32_bf16 v[178:181], v[22:25], v[6:9], v[178:181]
	v_mfma_f32_16x16x32_bf16 v[182:185], v[38:41], v[6:9], v[182:185]
	v_mfma_f32_16x16x32_bf16 v[186:189], v[54:57], v[6:9], v[186:189]
	v_mfma_f32_16x16x32_bf16 v[190:193], v[70:73], v[6:9], v[190:193]
	v_mfma_f32_16x16x32_bf16 v[194:197], v[86:89], v[6:9], v[194:197]
	v_mfma_f32_16x16x32_bf16 v[198:201], v[102:105], v[6:9], v[198:201]
	v_mfma_f32_16x16x32_bf16 v[202:205], v[118:121], v[6:9], v[202:205]
	v_mfma_f32_16x16x32_bf16 v[206:209], v[134:137], v[6:9], v[206:209]
	v_mfma_f32_16x16x32_bf16 v[178:181], v[26:29], v[10:13], v[178:181]
	v_mfma_f32_16x16x32_bf16 v[182:185], v[42:45], v[10:13], v[182:185]
	v_mfma_f32_16x16x32_bf16 v[186:189], v[58:61], v[10:13], v[186:189]
	v_mfma_f32_16x16x32_bf16 v[190:193], v[74:77], v[10:13], v[190:193]
	v_mfma_f32_16x16x32_bf16 v[194:197], v[90:93], v[10:13], v[194:197]
	v_mfma_f32_16x16x32_bf16 v[198:201], v[106:109], v[10:13], v[198:201]
	v_mfma_f32_16x16x32_bf16 v[202:205], v[122:125], v[10:13], v[202:205]
	v_mfma_f32_16x16x32_bf16 v[206:209], v[138:141], v[10:13], v[206:209]
	v_mfma_f32_16x16x32_bf16 v[178:181], v[30:33], v[14:17], v[178:181]
	v_mfma_f32_16x16x32_bf16 v[182:185], v[46:49], v[14:17], v[182:185]
	v_mfma_f32_16x16x32_bf16 v[186:189], v[62:65], v[14:17], v[186:189]
	v_mfma_f32_16x16x32_bf16 v[190:193], v[78:81], v[14:17], v[190:193]
	v_mfma_f32_16x16x32_bf16 v[194:197], v[94:97], v[14:17], v[194:197]
	v_mfma_f32_16x16x32_bf16 v[198:201], v[110:113], v[14:17], v[198:201]
	v_mfma_f32_16x16x32_bf16 v[202:205], v[126:129], v[14:17], v[202:205]
	v_mfma_f32_16x16x32_bf16 v[206:209], v[142:145], v[14:17], v[206:209]
	s_nop 7
	s_nop 3
	s_bitcmp1_b32 s4, 5
	s_cselect_b32 s35, 0xfe0, 32
	s_add_i32 s4, s4, s35
	s_cmpk_gt_i32 s4, 0x1fff
	s_cbranch_scc1 .Lp4n_nonext
; #define GAS __attribute__((address_space(1)))
; __device__ __forceinline__ void p4_load_a(P4Pre& P, const P4Ptr& p, int lane) {
;     const int r = lane & 15, g = lane >> 4, t = 16 * p.mt + r;
; #pragma unroll
;     for (int kb = 0; kb < 4; ++kb) P.ya[kb] = *(const GAS bf16x8*)(p.region + (size_t)((p.mt * 4 + kb) * 64 + lane) * 8);
; #pragma unroll
;     for (int vt = 0; vt < 4; ++vt)
; #pragma unroll
;         for (int kb = 0; kb < 4; ++kb) P.x[vt][kb] = *(const GAS bf16x8*)(p.sn + (size_t)((vt * 4 + kb) * 64 + lane) * 8);
; #pragma unroll
;     for (int vt = 0; vt < 8; ++vt) { P.ol[vt] = *(const GAS u64_t*)(p.oloc + (size_t)((vt * 4 + p.mt) * 64 + lane) * 4); P.gt8[vt] = *(const GAS u64_t*)(p.region + 24576 + t * 128 + 16 * vt + 4 * g); }
; }
; __device__ __forceinline__ void p4_run(int gw, int NGW, const bf16_t* HGR, const bf16_t* DNR, const bf16_t* OLH, const bf16_t* OLD, const bf16_t* BNB, const float* hg_nw, const float* dn_nw, bf16_t* OAB, int lane) {
;     ...
;         if (it + NGW < 8192) { p = p4_ptrs(it + NGW, HGR, DNR, OLH, OLD, BNB, hg_nw, dn_nw); p4_load_a(P, p, lane); }
;         asm volatile("" ::: "memory");
;         ss += __shfl_xor(ss, 16); ss += __shfl_xor(ss, 32);
;         const float rstd = rsqrtf(ss * (1.f / 128.f) + RMS_EPS);
	s_bfe_u32 s36, s4, 0xa0002
	s_bfe_u32 s47, s4, 0x20002
	s_cmpk_lt_u32 s4, 0x1000
	s_cselect_b32 s6, s26, s62
	s_cselect_b32 s7, s27, s63
	s_lshl_b32 s3, s36, 16
	s_add_u32 s28, s6, s3
	s_addc_u32 s29, s7, 0
	s_add_u32 s40, s28, 0x4000
	s_addc_u32 s41, s29, 0
	s_lshl_b32 s3, s36, 15
	s_add_u32 s42, s64, s3
	s_addc_u32 s43, s65, 0
	s_cmpk_lt_u32 s4, 0x1000
	s_cselect_b32 s40, s40, s42
	s_cselect_b32 s41, s41, s43
	s_add_u32 s42, s60, 0xf000000
	s_addc_u32 s43, s61, 0
	s_cmpk_lt_u32 s4, 0x1000
	s_cselect_b32 s42, s8, s42
	s_cselect_b32 s43, s9, s43
	s_lshl_b32 s3, s36, 14
	s_add_u32 s42, s42, s3
	s_addc_u32 s43, s43, 0
	s_lshl_b32 s3, s38, 9
	s_add_u32 s42, s42, s3
	s_addc_u32 s43, s43, 0
	s_lshl_b32 s3, s47, 9
	s_add_u32 s44, s24, s3
	s_addc_u32 s45, s25, 0
	s_cmpk_lt_u32 s4, 0x1000
	s_cselect_b32 s44, s44, s30
	s_cselect_b32 s45, s45, s31
	s_lshl_b32 s3, s38, 12
	s_add_u32 s50, s28, s3
	s_addc_u32 s51, s29, 0
	s_add_u32 s18, s50, 0xc000
	s_addc_u32 s19, s51, 0
	s_lshr_b32 s3, s36, 2
	s_lshl_b32 s3, s3, 2
	s_or_b32 s3, s3, s38
	s_lshl_b32 s3, s3, 16
	s_add_u32 s70, s10, s3
	s_addc_u32 s71, s11, 0
	s_lshr_b32 s3, s4, 12
	s_lshl_b32 s3, s3, 10
	s_lshl_b32 s33, s47, 8
	s_or_b32 s3, s3, s33
	s_add_u32 s70, s70, s3
	s_addc_u32 s71, s71, 0
	s_mov_b64 s[74:75], s[40:41]
	global_load_dwordx4 v[2:5], v210, s[50:51]
	global_load_dwordx4 v[6:9], v210, s[50:51] offset:1024
	global_load_dwordx4 v[10:13], v210, s[50:51] offset:2048
	global_load_dwordx4 v[14:17], v210, s[50:51] offset:3072
	global_load_dwordx4 v[22:25], v210, s[40:41] offset:1024
	global_load_dwordx4 v[26:29], v210, s[40:41] offset:2048
	global_load_dwordx4 v[30:33], v210, s[40:41] offset:3072
	s_add_u32 s40, s40, 0x1000
	s_addc_u32 s41, s41, 0
	global_load_dwordx4 v[38:41], v210, s[40:41] offset:1024
	global_load_dwordx4 v[42:45], v210, s[40:41] offset:2048
	global_load_dwordx4 v[46:49], v210, s[40:41] offset:3072
	s_add_u32 s40, s40, 0x1000
	s_addc_u32 s41, s41, 0
	global_load_dwordx4 v[54:57], v210, s[40:41] offset:1024
	global_load_dwordx4 v[58:61], v210, s[40:41] offset:2048
	global_load_dwordx4 v[62:65], v210, s[40:41] offset:3072
	s_add_u32 s40, s40, 0x1000
	s_addc_u32 s41, s41, 0
	global_load_dwordx4 v[70:73], v210, s[40:41] offset:1024
	global_load_dwordx4 v[74:77], v210, s[40:41] offset:2048
	global_load_dwordx4 v[78:81], v210, s[40:41] offset:3072
	s_add_u32 s40, s40, 0x1000
	s_addc_u32 s41, s41, 0
	global_load_dwordx4 v[86:89], v210, s[40:41] offset:1024
	global_load_dwordx4 v[90:93], v210, s[40:41] offset:2048
	global_load_dwordx4 v[94:97], v210, s[40:41] offset:3072
	s_add_u32 s40, s40, 0x1000
	s_addc_u32 s41, s41, 0
	global_load_dwordx4 v[102:105], v210, s[40:41] offset:1024
	global_load_dwordx4 v[106:109], v210, s[40:41] offset:2048
	global_load_dwordx4 v[110:113], v210, s[40:41] offset:3072
	s_add_u32 s40, s40, 0x1000
	s_addc_u32 s41, s41, 0
	global_load_dwordx4 v[118:121], v210, s[40:41] offset:1024
	global_load_dwordx4 v[122:125], v210, s[40:41] offset:2048
	global_load_dwordx4 v[126:129], v210, s[40:41] offset:3072
	s_add_u32 s40, s40, 0x1000
	s_addc_u32 s41, s41, 0
	global_load_dwordx4 v[134:137], v210, s[40:41] offset:1024
	global_load_dwordx4 v[138:141], v210, s[40:41] offset:2048
	global_load_dwordx4 v[142:145], v210, s[40:41] offset:3072
	global_load_dwordx2 v[146:147], v216, s[42:43]
	global_load_dwordx2 v[148:149], v216, s[42:43] offset:2048
	s_add_u32 s42, s42, 0x1000
	s_addc_u32 s43, s43, 0
	global_load_dwordx2 v[150:151], v216, s[42:43]
	global_load_dwordx2 v[152:153], v216, s[42:43] offset:2048
	s_add_u32 s42, s42, 0x1000
	s_addc_u32 s43, s43, 0
	global_load_dwordx2 v[154:155], v216, s[42:43]
	global_load_dwordx2 v[156:157], v216, s[42:43] offset:2048
	s_add_u32 s42, s42, 0x1000
	s_addc_u32 s43, s43, 0
	global_load_dwordx2 v[158:159], v216, s[42:43]
	global_load_dwordx2 v[160:161], v216, s[42:43] offset:2048
.Lp4n_nonext:
	v_mul_f32_e32 v229, v179, v179
	v_mul_f32_e32 v230, v181, v181
	v_fmac_f32_e32 v229, v178, v178
	v_fmac_f32_e32 v230, v180, v180
	v_add_f32_e32 v229, v229, v230
	v_mov_b32_e32 v228, v229
	v_mul_f32_e32 v229, v183, v183
	v_mul_f32_e32 v230, v185, v185
	v_fmac_f32_e32 v229, v182, v182
	v_fmac_f32_e32 v230, v184, v184
	v_add_f32_e32 v229, v229, v230
	v_add_f32_e32 v228, v228, v229
	v_mul_f32_e32 v229, v187, v187
	v_mul_f32_e32 v230, v189, v189
	v_fmac_f32_e32 v229, v186, v186
	v_fmac_f32_e32 v230, v188, v188
	v_add_f32_e32 v229, v229, v230
	v_add_f32_e32 v228, v228, v229
	v_mul_f32_e32 v229, v191, v191
	v_mul_f32_e32 v230, v193, v193
	v_fmac_f32_e32 v229, v190, v190
	v_fmac_f32_e32 v230, v192, v192
	v_add_f32_e32 v229, v229, v230
	v_add_f32_e32 v228, v228, v229
	v_mul_f32_e32 v229, v195, v195
	v_mul_f32_e32 v230, v197, v197
	v_fmac_f32_e32 v229, v194, v194
	v_fmac_f32_e32 v230, v196, v196
	v_add_f32_e32 v229, v229, v230
	v_add_f32_e32 v228, v228, v229
	v_mul_f32_e32 v229, v199, v199
	v_mul_f32_e32 v230, v201, v201
	v_fmac_f32_e32 v229, v198, v198
	v_fmac_f32_e32 v230, v200, v200
	v_add_f32_e32 v229, v229, v230
	v_add_f32_e32 v228, v228, v229
	v_mul_f32_e32 v229, v203, v203
	v_mul_f32_e32 v230, v205, v205
	v_fmac_f32_e32 v229, v202, v202
	v_fmac_f32_e32 v230, v204, v204
	v_add_f32_e32 v229, v229, v230
	v_add_f32_e32 v228, v228, v229
	v_mul_f32_e32 v229, v207, v207
	v_mul_f32_e32 v230, v209, v209
	v_fmac_f32_e32 v229, v206, v206
	v_fmac_f32_e32 v230, v208, v208
	v_add_f32_e32 v229, v229, v230
	v_add_f32_e32 v228, v228, v229
	ds_bpermute_b32 v229, v217, v228
	s_waitcnt lgkmcnt(0)
	v_add_f32_e32 v228, v228, v229
	ds_bpermute_b32 v229, v218, v228
	s_waitcnt lgkmcnt(0)
	v_add_f32_e32 v228, v228, v229
	v_fmamk_f32 v228, v228, 0x3c000000, v219
	v_rsq_f32_e32 v232, v228
	v_mov_b32_e32 v233, 0
	s_cmpk_gt_i32 s4, 0x1fff
	s_cbranch_scc1 .Lp4n_w0
	s_waitcnt vmcnt(36)
	s_branch .Lp4n_tail
